# P9 cross-attention scores: all eight Q fragments of a chunk loaded at the top of the chunk (both 128-byte lines of each row open together), four extra quads v238-v253
# baseline (speedup 1.0000x reference)
; #define LAS __attribute__((address_space(3)))
; #define MFMA32(a, b, c) __builtin_amdgcn_mfma_f32_32x32x16_bf16((a), (b), (c), 0, 0, 0)
; __device__ __forceinline__ void xa_item(int it, LAS unsigned char* lds, const bf16_t* XQ, const bf16_t* XK, bf16_t* PB, int tid, int wid, int lane) {
;     ...
;         if (wid < 4) {
; #pragma unroll 2
;             for (int ks = 0; ks < 8; ++ks) {
;                 const bf16x8 qv = *(const bf16x8*)(qp + c * 128 + 16 * ks);
; #pragma unroll
;                 for (int mt = 0; mt < 8; ++mt) st[mt] = MFMA32(*(const LAS bf16x8*)(KL + (32 * mt + x) * KS + 16 * ks + 8 * hi), qv, st[mt]);
;             }
.LBB0_1517:
	global_load_dwordx4 v[6:9], v[4:5], off offset:-32
	global_load_dwordx4 v[238:241], v[4:5], off offset:96
	global_load_dwordx4 v[10:13], v[4:5], off
	global_load_dwordx4 v[230:233], v[4:5], off offset:32
	global_load_dwordx4 v[234:237], v[4:5], off offset:64
	global_load_dwordx4 v[242:245], v[4:5], off offset:128
	global_load_dwordx4 v[246:249], v[4:5], off offset:160
	global_load_dwordx4 v[250:253], v[4:5], off offset:192
	s_mov_b32 s6, 0
	v_add_u32_e32 v3, s6, v195
	ds_read_b128 v[14:17], v3
	ds_read_b128 v[198:201], v3 offset:32
	v_add_u32_e32 v185, s6, v194
	v_add_u32_e32 v210, s6, v193
	v_add_u32_e32 v218, s6, v192
	v_add_u32_e32 v226, s6, v191
	s_waitcnt vmcnt(7) lgkmcnt(1)
	v_mfma_f32_32x32x16_bf16 v[130:145], v[14:17], v[6:9], v[130:145]
	ds_read_b128 v[14:17], v185
	ds_read_b128 v[202:205], v185 offset:32
	s_waitcnt lgkmcnt(1)
	v_mfma_f32_32x32x16_bf16 v[114:129], v[14:17], v[6:9], v[114:129]
	ds_read_b128 v[14:17], v3 offset:17408
	ds_read_b128 v[206:209], v3 offset:17440
	s_waitcnt lgkmcnt(1)
	v_mfma_f32_32x32x16_bf16 v[98:113], v[14:17], v[6:9], v[98:113]
	ds_read_b128 v[14:17], v210
	ds_read_b128 v[210:213], v210 offset:32
	s_waitcnt lgkmcnt(1)
	v_mfma_f32_32x32x16_bf16 v[82:97], v[14:17], v[6:9], v[82:97]
	ds_read_b128 v[14:17], v3 offset:34816
	ds_read_b128 v[214:217], v3 offset:34848
	s_waitcnt lgkmcnt(1)
	v_mfma_f32_32x32x16_bf16 v[66:81], v[14:17], v[6:9], v[66:81]
	ds_read_b128 v[14:17], v218
	ds_read_b128 v[218:221], v218 offset:32
	s_waitcnt lgkmcnt(1)
	v_mfma_f32_32x32x16_bf16 v[50:65], v[14:17], v[6:9], v[50:65]
	ds_read_b128 v[14:17], v3 offset:52224
	ds_read_b128 v[222:225], v3 offset:52256
	s_waitcnt lgkmcnt(1)
	v_mfma_f32_32x32x16_bf16 v[34:49], v[14:17], v[6:9], v[34:49]
	ds_read_b128 v[14:17], v226
	ds_read_b128 v[226:229], v226 offset:32
	s_waitcnt lgkmcnt(1)
	v_mfma_f32_32x32x16_bf16 v[18:33], v[14:17], v[6:9], v[18:33]
	s_waitcnt vmcnt(5)
	v_mfma_f32_32x32x16_bf16 v[130:145], v[198:201], v[10:13], v[130:145]
	v_mfma_f32_32x32x16_bf16 v[114:129], v[202:205], v[10:13], v[114:129]
	v_mfma_f32_32x32x16_bf16 v[98:113], v[206:209], v[10:13], v[98:113]
	v_mfma_f32_32x32x16_bf16 v[82:97], v[210:213], v[10:13], v[82:97]
	v_mfma_f32_32x32x16_bf16 v[66:81], v[214:217], v[10:13], v[66:81]
	v_mfma_f32_32x32x16_bf16 v[50:65], v[218:221], v[10:13], v[50:65]
	v_mfma_f32_32x32x16_bf16 v[34:49], v[222:225], v[10:13], v[34:49]
	s_waitcnt lgkmcnt(0)
	v_mfma_f32_32x32x16_bf16 v[18:33], v[226:229], v[10:13], v[18:33]
	s_mov_b32 s6, 64
	v_add_u32_e32 v3, s6, v195
	ds_read_b128 v[14:17], v3
	ds_read_b128 v[198:201], v3 offset:32
	v_add_u32_e32 v185, s6, v194
	v_add_u32_e32 v210, s6, v193
	v_add_u32_e32 v218, s6, v192
	v_add_u32_e32 v226, s6, v191
	s_waitcnt vmcnt(4) lgkmcnt(1)
	v_mfma_f32_32x32x16_bf16 v[130:145], v[14:17], v[230:233], v[130:145]
	ds_read_b128 v[14:17], v185
	ds_read_b128 v[202:205], v185 offset:32
	s_waitcnt lgkmcnt(1)
	v_mfma_f32_32x32x16_bf16 v[114:129], v[14:17], v[230:233], v[114:129]
	ds_read_b128 v[14:17], v3 offset:17408
	ds_read_b128 v[206:209], v3 offset:17440
	s_waitcnt lgkmcnt(1)
	v_mfma_f32_32x32x16_bf16 v[98:113], v[14:17], v[230:233], v[98:113]
	ds_read_b128 v[14:17], v210
	ds_read_b128 v[210:213], v210 offset:32
	s_waitcnt lgkmcnt(1)
	v_mfma_f32_32x32x16_bf16 v[82:97], v[14:17], v[230:233], v[82:97]
	ds_read_b128 v[14:17], v3 offset:34816
	ds_read_b128 v[214:217], v3 offset:34848
	s_waitcnt lgkmcnt(1)
	v_mfma_f32_32x32x16_bf16 v[66:81], v[14:17], v[230:233], v[66:81]
	ds_read_b128 v[14:17], v218
	ds_read_b128 v[218:221], v218 offset:32
	s_waitcnt lgkmcnt(1)
	v_mfma_f32_32x32x16_bf16 v[50:65], v[14:17], v[230:233], v[50:65]
	ds_read_b128 v[14:17], v3 offset:52224
	ds_read_b128 v[222:225], v3 offset:52256
	s_waitcnt lgkmcnt(1)
	v_mfma_f32_32x32x16_bf16 v[34:49], v[14:17], v[230:233], v[34:49]
	ds_read_b128 v[14:17], v226
	ds_read_b128 v[226:229], v226 offset:32
	s_waitcnt lgkmcnt(1)
	v_mfma_f32_32x32x16_bf16 v[18:33], v[14:17], v[230:233], v[18:33]
	s_waitcnt vmcnt(3)
	v_mfma_f32_32x32x16_bf16 v[130:145], v[198:201], v[234:237], v[130:145]
	v_mfma_f32_32x32x16_bf16 v[114:129], v[202:205], v[234:237], v[114:129]
	v_mfma_f32_32x32x16_bf16 v[98:113], v[206:209], v[234:237], v[98:113]
	v_mfma_f32_32x32x16_bf16 v[82:97], v[210:213], v[234:237], v[82:97]
	v_mfma_f32_32x32x16_bf16 v[66:81], v[214:217], v[234:237], v[66:81]
	v_mfma_f32_32x32x16_bf16 v[50:65], v[218:221], v[234:237], v[50:65]
	v_mfma_f32_32x32x16_bf16 v[34:49], v[222:225], v[234:237], v[34:49]
	s_waitcnt lgkmcnt(0)
; #define LAS __attribute__((address_space(3)))
; #define MFMA32(a, b, c) __builtin_amdgcn_mfma_f32_32x32x16_bf16((a), (b), (c), 0, 0, 0)
; __device__ __forceinline__ void xa_item(int it, LAS unsigned char* lds, const bf16_t* XQ, const bf16_t* XK, bf16_t* PB, int tid, int wid, int lane) {
;     ...
;         if (wid < 4) {
; #pragma unroll 2
;             for (int ks = 0; ks < 8; ++ks) {
;                 const bf16x8 qv = *(const bf16x8*)(qp + c * 128 + 16 * ks);
; #pragma unroll
;                 for (int mt = 0; mt < 8; ++mt) st[mt] = MFMA32(*(const LAS bf16x8*)(KL + (32 * mt + x) * KS + 16 * ks + 8 * hi), qv, st[mt]);
;             }
	v_mfma_f32_32x32x16_bf16 v[18:33], v[226:229], v[234:237], v[18:33]
	s_mov_b32 s6, 128
	v_add_u32_e32 v3, s6, v195
	ds_read_b128 v[14:17], v3
	ds_read_b128 v[198:201], v3 offset:32
	v_add_u32_e32 v185, s6, v194
	v_add_u32_e32 v210, s6, v193
	v_add_u32_e32 v218, s6, v192
	v_add_u32_e32 v226, s6, v191
	s_waitcnt vmcnt(6) lgkmcnt(1)
	v_mfma_f32_32x32x16_bf16 v[130:145], v[14:17], v[238:241], v[130:145]
	ds_read_b128 v[14:17], v185
	ds_read_b128 v[202:205], v185 offset:32
	s_waitcnt lgkmcnt(1)
	v_mfma_f32_32x32x16_bf16 v[114:129], v[14:17], v[238:241], v[114:129]
	ds_read_b128 v[14:17], v3 offset:17408
	ds_read_b128 v[206:209], v3 offset:17440
	s_waitcnt lgkmcnt(1)
	v_mfma_f32_32x32x16_bf16 v[98:113], v[14:17], v[238:241], v[98:113]
	ds_read_b128 v[14:17], v210
	ds_read_b128 v[210:213], v210 offset:32
	s_waitcnt lgkmcnt(1)
	v_mfma_f32_32x32x16_bf16 v[82:97], v[14:17], v[238:241], v[82:97]
	ds_read_b128 v[14:17], v3 offset:34816
	ds_read_b128 v[214:217], v3 offset:34848
	s_waitcnt lgkmcnt(1)
	v_mfma_f32_32x32x16_bf16 v[66:81], v[14:17], v[238:241], v[66:81]
	ds_read_b128 v[14:17], v218
	ds_read_b128 v[218:221], v218 offset:32
	s_waitcnt lgkmcnt(1)
	v_mfma_f32_32x32x16_bf16 v[50:65], v[14:17], v[238:241], v[50:65]
	ds_read_b128 v[14:17], v3 offset:52224
	ds_read_b128 v[222:225], v3 offset:52256
	s_waitcnt lgkmcnt(1)
	v_mfma_f32_32x32x16_bf16 v[34:49], v[14:17], v[238:241], v[34:49]
	ds_read_b128 v[14:17], v226
	ds_read_b128 v[226:229], v226 offset:32
	s_waitcnt lgkmcnt(1)
	v_mfma_f32_32x32x16_bf16 v[18:33], v[14:17], v[238:241], v[18:33]
	s_waitcnt vmcnt(2)
	v_mfma_f32_32x32x16_bf16 v[130:145], v[198:201], v[242:245], v[130:145]
	v_mfma_f32_32x32x16_bf16 v[114:129], v[202:205], v[242:245], v[114:129]
	v_mfma_f32_32x32x16_bf16 v[98:113], v[206:209], v[242:245], v[98:113]
	v_mfma_f32_32x32x16_bf16 v[82:97], v[210:213], v[242:245], v[82:97]
	v_mfma_f32_32x32x16_bf16 v[66:81], v[214:217], v[242:245], v[66:81]
	v_mfma_f32_32x32x16_bf16 v[50:65], v[218:221], v[242:245], v[50:65]
	v_mfma_f32_32x32x16_bf16 v[34:49], v[222:225], v[242:245], v[34:49]
	s_waitcnt lgkmcnt(0)
	v_mfma_f32_32x32x16_bf16 v[18:33], v[226:229], v[242:245], v[18:33]
	s_mov_b32 s6, 192
	v_add_u32_e32 v3, s6, v195
	ds_read_b128 v[14:17], v3
	ds_read_b128 v[198:201], v3 offset:32
	v_add_u32_e32 v185, s6, v194
	v_add_u32_e32 v210, s6, v193
	v_add_u32_e32 v218, s6, v192
	v_add_u32_e32 v226, s6, v191
	s_waitcnt vmcnt(1) lgkmcnt(1)
	v_mfma_f32_32x32x16_bf16 v[130:145], v[14:17], v[246:249], v[130:145]
	ds_read_b128 v[14:17], v185
	ds_read_b128 v[202:205], v185 offset:32
	s_waitcnt lgkmcnt(1)
	v_mfma_f32_32x32x16_bf16 v[114:129], v[14:17], v[246:249], v[114:129]
	ds_read_b128 v[14:17], v3 offset:17408
	ds_read_b128 v[206:209], v3 offset:17440
	s_waitcnt lgkmcnt(1)
	v_mfma_f32_32x32x16_bf16 v[98:113], v[14:17], v[246:249], v[98:113]
	ds_read_b128 v[14:17], v210
	ds_read_b128 v[210:213], v210 offset:32
	s_waitcnt lgkmcnt(1)
	v_mfma_f32_32x32x16_bf16 v[82:97], v[14:17], v[246:249], v[82:97]
	ds_read_b128 v[14:17], v3 offset:34816
	ds_read_b128 v[214:217], v3 offset:34848
	s_waitcnt lgkmcnt(1)
	v_mfma_f32_32x32x16_bf16 v[66:81], v[14:17], v[246:249], v[66:81]
	ds_read_b128 v[14:17], v218
	ds_read_b128 v[218:221], v218 offset:32
	s_waitcnt lgkmcnt(1)
	v_mfma_f32_32x32x16_bf16 v[50:65], v[14:17], v[246:249], v[50:65]
	ds_read_b128 v[14:17], v3 offset:52224
	ds_read_b128 v[222:225], v3 offset:52256
	s_waitcnt lgkmcnt(1)
	v_mfma_f32_32x32x16_bf16 v[34:49], v[14:17], v[246:249], v[34:49]
	ds_read_b128 v[14:17], v226
	ds_read_b128 v[226:229], v226 offset:32
	s_waitcnt lgkmcnt(1)
	v_mfma_f32_32x32x16_bf16 v[18:33], v[14:17], v[246:249], v[18:33]
	s_waitcnt vmcnt(0)
	v_mfma_f32_32x32x16_bf16 v[130:145], v[198:201], v[250:253], v[130:145]
	v_mfma_f32_32x32x16_bf16 v[114:129], v[202:205], v[250:253], v[114:129]
	v_mfma_f32_32x32x16_bf16 v[98:113], v[206:209], v[250:253], v[98:113]
	v_mfma_f32_32x32x16_bf16 v[82:97], v[210:213], v[250:253], v[82:97]
	v_mfma_f32_32x32x16_bf16 v[66:81], v[214:217], v[250:253], v[66:81]
	v_mfma_f32_32x32x16_bf16 v[50:65], v[218:221], v[250:253], v[50:65]
	v_mfma_f32_32x32x16_bf16 v[34:49], v[222:225], v[250:253], v[34:49]
	s_waitcnt lgkmcnt(0)
	v_mfma_f32_32x32x16_bf16 v[18:33], v[226:229], v[250:253], v[18:33]
	s_branch .LBB0_1512
